# scheduler arithmetic: generic r/gsz division (gsz is always 8 at M=32768) replaced by shift/mask in 9 unit-loop headers
# baseline (speedup 1.0000x reference)
.LBB0_255:
	s_ashr_i32 s4, s26, 3
	s_add_i32 s4, s28, s4
	s_ashr_i32 s5, s4, 31
	s_lshr_b32 s5, s5, 27
	s_add_i32 s5, s4, s5
	s_ashr_i32 s10, s5, 5
	s_lshl_b32 s10, s10, 3
	s_sub_i32 s11, 0x80, s10
	s_min_i32 s11, s11, 8
	s_andn2_b32 s5, s5, 31
	s_sub_i32 s4, s4, s5
	s_lshr_b32 s66, s4, 3
	s_and_b32 s4, s4, 7
	s_add_i32 s67, s10, s4

.LBB0_298:
	s_ashr_i32 s4, s26, 3
	s_add_i32 s4, s28, s4
	s_ashr_i32 s5, s4, 31
	s_lshr_b32 s5, s5, 27
	s_add_i32 s5, s4, s5
	s_ashr_i32 s10, s5, 5
	s_lshl_b32 s10, s10, 3
	s_sub_i32 s11, 0x80, s10
	s_min_i32 s11, s11, 8
	s_andn2_b32 s5, s5, 31
	s_sub_i32 s4, s4, s5
	s_lshr_b32 s67, s4, 3
	s_and_b32 s4, s4, 7
	s_add_i32 s68, s10, s4

.LBB0_386:
	s_add_i32 s62, s62, 1
	s_mul_i32 s4, s62, s73
	s_mul_hi_u32 s5, s62, s72
	s_add_i32 s5, s5, s4
	s_mul_i32 s4, s62, s72
	s_add_u32 s10, s4, s2
	s_addc_u32 s11, s5, s3
	v_cmp_gt_i64_e32 vcc, s[10:11], v[184:185]
	v_cmp_lt_i64_e64 s[44:45], s[10:11], v[182:183]
	s_cbranch_vccnz .LBB0_388
	s_ashr_i32 s4, s10, 31
	s_lshr_b32 s4, s4, 29
	s_add_i32 s4, s10, s4
	s_ashr_i32 s5, s4, 3
	s_and_b32 s4, s4, -8
	s_sub_i32 s4, s10, s4
	s_cmp_lt_i32 s4, 0
	s_cselect_b32 s10, s53, 0x160
	s_mul_i32 s4, s4, s10
	s_add_i32 s4, s4, s5
	s_mul_hi_i32 s5, s4, 0x2e8ba2e9
	s_lshr_b32 s10, s5, 31
	s_ashr_i32 s5, s5, 5
	s_add_i32 s5, s5, s10
	s_lshl_b32 s10, s5, 3
	s_sub_i32 s11, 0x80, s10
	s_min_i32 s11, s11, 8
	s_mulk_i32 s5, 0xb0
	s_sub_i32 s4, s4, s5
	s_lshr_b32 s63, s4, 3
	s_and_b32 s4, s4, 7
	s_add_i32 s66, s10, s4

.LBB0_468:
	s_ashr_i32 s4, s24, 3
	s_add_i32 s4, s26, s4
	s_ashr_i32 s5, s4, 31
	s_lshr_b32 s5, s5, 27
	s_add_i32 s5, s4, s5
	s_ashr_i32 s10, s5, 5
	s_lshl_b32 s10, s10, 3
	s_sub_i32 s11, 0x80, s10
	s_min_i32 s11, s11, 8
	s_andn2_b32 s5, s5, 31
	s_sub_i32 s4, s4, s5
	s_lshr_b32 s63, s4, 3
	s_and_b32 s4, s4, 7
	s_add_i32 s66, s10, s4

.LBB0_791:
	s_ashr_i32 s10, s24, 3
	s_add_i32 s10, s26, s10
	s_ashr_i32 s11, s10, 31
	s_lshr_b32 s11, s11, 27
	s_add_i32 s11, s10, s11
	s_ashr_i32 s24, s11, 5
	s_lshl_b32 s24, s24, 3
	s_sub_i32 s25, 0x80, s24
	s_min_i32 s25, s25, 8
	s_andn2_b32 s11, s11, 31
	s_sub_i32 s10, s10, s11
	s_lshr_b32 s52, s10, 3
	s_and_b32 s10, s10, 7
	s_add_i32 s56, s24, s10

.LBB0_836:
	s_add_i32 s59, s59, 1
	s_mul_i32 s10, s59, s73
	s_mul_hi_u32 s11, s59, s72
	s_add_i32 s11, s11, s10
	s_mul_i32 s10, s59, s72
	s_add_u32 s10, s10, s2
	s_addc_u32 s11, s11, s3
	v_cmp_gt_i64_e32 vcc, s[10:11], v[188:189]
	v_cmp_lt_i64_e64 s[42:43], s[10:11], v[186:187]
	s_cbranch_vccnz .LBB0_838
	s_ashr_i32 s11, s10, 31
	s_lshr_b32 s11, s11, 29
	s_add_i32 s11, s10, s11
	s_ashr_i32 s16, s11, 3
	s_and_b32 s11, s11, -8
	s_sub_i32 s10, s10, s11
	s_cmp_lt_i32 s10, 0
	s_cselect_b32 s11, s97, 0x60
	s_mul_i32 s10, s10, s11
	s_add_i32 s10, s10, s16
	s_mul_hi_i32 s11, s10, 0x2aaaaaab
	s_lshr_b32 s16, s11, 31
	s_ashr_i32 s11, s11, 3
	s_add_i32 s11, s11, s16
	s_lshl_b32 s16, s11, 3
	s_sub_i32 s17, 0x80, s16
	s_min_i32 s17, s17, 8
	s_mul_i32 s11, s11, 48
	s_sub_i32 s10, s10, s11
	s_lshr_b32 s60, s10, 3
	s_and_b32 s10, s10, 7
	s_add_i32 s61, s16, s10

.LBB0_1046:
	s_ashr_i32 s10, s16, 3
	s_add_i32 s10, s24, s10
	s_ashr_i32 s11, s10, 31
	s_lshr_b32 s11, s11, 27
	s_add_i32 s11, s10, s11
	s_ashr_i32 s16, s11, 5
	s_lshl_b32 s16, s16, 3
	s_sub_i32 s17, 0x80, s16
	s_min_i32 s17, s17, 8
	s_andn2_b32 s11, s11, 31
	s_sub_i32 s10, s10, s11
	s_lshr_b32 s58, s10, 3
	s_and_b32 s10, s10, 7
	s_add_i32 s59, s16, s10

.LBB0_1134:
	s_add_i32 s57, s57, 1
	s_mul_i32 s10, s57, s73
	s_mul_hi_u32 s11, s57, s72
	s_add_i32 s11, s11, s10
	s_mul_i32 s10, s57, s72
	s_add_u32 s10, s10, s2
	s_addc_u32 s11, s11, s3
	v_cmp_gt_i64_e32 vcc, s[10:11], v[192:193]
	v_cmp_lt_i64_e64 s[44:45], s[10:11], v[190:191]
	s_cbranch_vccnz .LBB0_1136
	s_ashr_i32 s11, s10, 31
	s_lshr_b32 s11, s11, 29
	s_add_i32 s11, s10, s11
	s_ashr_i32 s16, s11, 3
	s_and_b32 s11, s11, -8
	s_sub_i32 s10, s10, s11
	s_cmp_lt_i32 s10, 0
	s_movk_i32 s11, 0x161
	s_cselect_b32 s11, s11, 0x160
	s_mul_i32 s10, s10, s11
	s_add_i32 s10, s10, s16
	s_mul_hi_i32 s11, s10, 0x2e8ba2e9
	s_lshr_b32 s16, s11, 31
	s_ashr_i32 s11, s11, 5
	s_add_i32 s11, s11, s16
	s_lshl_b32 s16, s11, 3
	s_sub_i32 s17, 0x80, s16
	s_min_i32 s17, s17, 8
	s_mulk_i32 s11, 0xb0
	s_sub_i32 s10, s10, s11
	s_lshr_b32 s58, s10, 3
	s_and_b32 s10, s10, 7
	s_add_i32 s59, s16, s10

.LBB0_1217:
	s_ashr_i32 s10, s22, 3
	s_add_i32 s10, s24, s10
	s_ashr_i32 s11, s10, 31
	s_lshr_b32 s11, s11, 27
	s_add_i32 s11, s10, s11
	s_ashr_i32 s22, s11, 5
	s_lshl_b32 s22, s22, 3
	s_sub_i32 s23, 0x80, s22
	s_min_i32 s23, s23, 8
	s_andn2_b32 s11, s11, 31
	s_sub_i32 s10, s10, s11
	s_lshr_b32 s56, s10, 3
	s_and_b32 s10, s10, 7
	s_add_i32 s57, s22, s10
